# ml_local load hoist + batched NL LDS reads + straight-line attention tile body (scores/softmax/PV)
# speedup vs baseline: 1.0161x; 1.0161x over previous
; DEV float fsilu(float x) { return x * fsigmoid(x); }
; DEV bf16x8 pack8(const float* x) { u32x4 o; o.x = pk2(x[0], x[1]); o.y = pk2(x[2], x[3]); o.z = pk2(x[4], x[5]); o.w = pk2(x[6], x[7]); return __builtin_bit_cast(bf16x8, o); }
; DEV void conv_silu8(const Fr& F, int seqrow0, int seqlen, int p, int zc, const float* cw, float scale, float* o) {
;     float a[8], x[8];
; #pragma unroll
;     for (int j = 0; j < 8; ++j) a[j] = 0.f;
; #pragma unroll
;     for (int tap = 0; tap < 3; ++tap) { const int pp = p + tap - 1; if (pp >= 0 && pp < seqlen) { unpack8(*(const u32x4*)(F.Z + (size_t)(seqrow0 + pp) * ZS + zc), x);
;         const f32x4 w0 = *(const f32x4*)(cw + tap * 512), w1 = *(const f32x4*)(cw + tap * 512 + 4);
; #pragma unroll
;         for (int j = 0; j < 4; ++j) { a[j] += x[j] * w0[j]; a[4 + j] += x[4 + j] * w1[j]; } } }
; #pragma unroll
;     for (int j = 0; j < 8; ++j) o[j] = fsilu(a[j]) * scale;
; }
; DEV void ml_local_item(const Fr& F, int l, int b, int ch, int h) {
;     ...
;     u32x4 vv[2]; float kk[2][8];
; #pragma unroll
;     for (int i = 0; i < 2; ++i) { const int idx = tid + NTHR * i; const int s = idx >> 3, c8 = (idx & 7) * 8;
;         vv[i] = *(const u32x4*)(F.Z + (size_t)(row0 + s) * ZS + ZC_MV + h * 64 + c8);
;         conv_silu8(F, seqrow0, seqlen, p0 + s, ZC_MK + h * 64 + c8, F.in[I_CONVW] + l * 1536 + 256 + h * 64 + c8, 0.125f, kk[i]);
;         *(bf16x8*)(F.A + (size_t)(row0 + s) * 256 + h * 64 + c8) = pack8(kk[i]); }
.LBB0_316:
	s_add_i32 s8, s7, 0xffffff00
	s_cmp_lt_i32 s18, 2
	s_movk_i32 s9, 0x4000
	v_add_u32_e32 v6, s29, v48
	v_mov_b64_e32 v[2:3], s[78:79]
	s_cselect_b32 s27, 0x100, s9
	s_cselect_b32 s30, 0, 0x100
	s_cselect_b32 s31, s7, s8
	v_mad_i64_i32 v[2:3], s[8:9], v6, s53, v[2:3]
	s_lshl_b32 s60, s26, 7
	v_lshl_add_u64 v[2:3], v[2:3], 0, s[60:61]
	v_mov_b32_e32 v31, v0
	v_lshl_add_u64 v[2:3], v[2:3], 0, v[30:31]
	global_load_dwordx4 v[2:5], v[2:3], off offset:2048
	s_lshl_b32 s33, s26, 6
	v_or_b32_e32 v8, s33, v18
	v_add_u32_e32 v7, s31, v48
	s_add_i32 s30, s30, s6
	s_lshl_b32 s60, s26, 8
	v_lshlrev_b32_e32 v8, 1, v8
	v_mov_b32_e32 v9, v0
	v_cmp_lt_i32_e32 vcc, 0, v7
	v_cmp_ge_i32_e64 s[8:9], s27, v7
	s_add_i32 s28, s30, -1
	v_lshl_add_u64 v[16:17], v[20:21], 0, s[60:61]
	v_lshl_add_u64 v[14:15], s[78:79], 0, v[8:9]
	s_and_b64 s[8:9], vcc, s[8:9]
	v_mov_b32_e32 v33, 0
	v_mov_b32_e32 v38, 0
	v_mov_b32_e32 v39, 0
	v_mov_b32_e32 v36, 0
	v_mov_b32_e32 v37, 0
	v_mov_b32_e32 v8, 0
	v_mov_b32_e32 v9, 0
	v_mov_b32_e32 v40, 0
	v_mov_b32_e32 v41, 0
	v_add_u32_e32 v243, s31, v49
	global_load_dwordx4 v[156:159], v[16:17], off offset:1024
	global_load_dwordx4 v[160:163], v[16:17], off offset:1040
	global_load_dwordx4 v[164:167], v[16:17], off offset:3072
	global_load_dwordx4 v[168:171], v[16:17], off offset:3088
	s_mov_b64 s[100:101], 0x1000
	v_lshl_add_u64 v[244:245], v[16:17], 0, s[100:101]
	global_load_dwordx4 v[172:175], v[244:245], off offset:1024
	global_load_dwordx4 v[176:179], v[244:245], off offset:1040
	v_cmp_lt_i32_e32 vcc, 0, v7
	v_cmp_ge_i32_e64 s[100:101], s27, v7
	s_and_b64 vcc, vcc, s[100:101]
	s_and_saveexec_b64 s[100:101], vcc
	s_cbranch_execz .Lmlc_a0
	v_add_u32_e32 v246, s28, v7
	v_mad_i64_i32 v[246:247], vcc, v246, s53, v[14:15]
	global_load_dwordx4 v[180:183], v[246:247], off offset:1536
.Lmlc_a0:
	s_or_b64 exec, exec, s[100:101]
	v_cmp_gt_u32_e32 vcc, s27, v7
	s_and_saveexec_b64 s[100:101], vcc
	s_cbranch_execz .Lmlc_a1
	v_add_u32_e32 v246, s30, v7
	v_mad_i64_i32 v[246:247], vcc, v246, s53, v[14:15]
	global_load_dwordx4 v[184:187], v[246:247], off offset:1536
.Lmlc_a1:
	s_or_b64 exec, exec, s[100:101]
	v_add_u32_e32 v248, 2, v7
	v_cmp_lt_i32_e32 vcc, -2, v7
	v_cmp_ge_i32_e64 s[100:101], s27, v248
	s_and_b64 vcc, vcc, s[100:101]
	s_and_saveexec_b64 s[100:101], vcc
	s_cbranch_execz .Lmlc_a2
	v_add_u32_e32 v246, s28, v248
	v_mad_i64_i32 v[246:247], vcc, v246, s53, v[14:15]
	global_load_dwordx4 v[80:83], v[246:247], off offset:1536
.Lmlc_a2:
	s_or_b64 exec, exec, s[100:101]
	v_cmp_lt_i32_e32 vcc, 0, v243
	v_cmp_ge_i32_e64 s[100:101], s27, v243
	s_and_b64 vcc, vcc, s[100:101]
	s_and_saveexec_b64 s[100:101], vcc
	s_cbranch_execz .Lmlc_b0
	v_add_u32_e32 v246, s28, v243
	v_mad_i64_i32 v[246:247], vcc, v246, s53, v[14:15]
	global_load_dwordx4 v[84:87], v[246:247], off offset:1536
.Lmlc_b0:
	s_or_b64 exec, exec, s[100:101]
	v_cmp_gt_u32_e32 vcc, s27, v243
	s_and_saveexec_b64 s[100:101], vcc
	s_cbranch_execz .Lmlc_b1
	v_add_u32_e32 v246, s30, v243
	v_mad_i64_i32 v[246:247], vcc, v246, s53, v[14:15]
	global_load_dwordx4 v[88:91], v[246:247], off offset:1536
.Lmlc_b1:
	s_or_b64 exec, exec, s[100:101]
	v_add_u32_e32 v248, 2, v243
	v_cmp_lt_i32_e32 vcc, -2, v243
	v_cmp_ge_i32_e64 s[100:101], s27, v248
	s_and_b64 vcc, vcc, s[100:101]
	s_and_saveexec_b64 s[100:101], vcc
	s_cbranch_execz .Lmlc_b2
	v_add_u32_e32 v246, s28, v248
	v_mad_i64_i32 v[246:247], vcc, v246, s53, v[14:15]
	global_load_dwordx4 v[92:95], v[246:247], off offset:1536
.Lmlc_b2:
	s_or_b64 exec, exec, s[100:101]
	s_waitcnt vmcnt(0)
	s_and_saveexec_b64 s[6:7], s[8:9]
	s_cbranch_execz .LBB0_318
	v_lshlrev_b32_e32 v8, 16, v180
	v_and_b32_e32 v9, 0xffff0000, v180
	v_lshlrev_b32_e32 v32, 16, v181
	v_and_b32_e32 v33, 0xffff0000, v181
	v_pk_fma_f32 v[36:37], v[158:159], v[32:33], 0 op_sel_hi:[1,1,0]
	v_lshlrev_b32_e32 v32, 16, v183
	v_and_b32_e32 v33, 0xffff0000, v183
	v_pk_fma_f32 v[38:39], v[156:157], v[8:9], 0 op_sel_hi:[1,1,0]
	v_lshlrev_b32_e32 v8, 16, v182
	v_and_b32_e32 v9, 0xffff0000, v182
	v_pk_fma_f32 v[32:33], v[162:163], v[32:33], 0 op_sel_hi:[1,1,0]
	v_pk_fma_f32 v[8:9], v[160:161], v[8:9], 0 op_sel_hi:[1,1,0]
	v_mov_b32_e32 v40, v32
	v_mov_b32_e32 v41, v33
.LBB0_318:
	s_or_b64 exec, exec, s[6:7]
	v_cmp_gt_u32_e32 vcc, s27, v7
	s_and_saveexec_b64 s[6:7], vcc
	s_cbranch_execz .LBB0_320
	v_lshlrev_b32_e32 v34, 16, v184
	v_and_b32_e32 v35, 0xffff0000, v184
	v_pk_fma_f32 v[38:39], v[164:165], v[34:35], v[38:39]
	v_lshlrev_b32_e32 v34, 16, v186
	v_and_b32_e32 v35, 0xffff0000, v186
	v_pk_fma_f32 v[8:9], v[168:169], v[34:35], v[8:9]
	v_lshlrev_b32_e32 v34, 16, v185
	v_and_b32_e32 v35, 0xffff0000, v185
	v_pk_fma_f32 v[36:37], v[166:167], v[34:35], v[36:37]
	v_lshlrev_b32_e32 v34, 16, v187
	v_and_b32_e32 v35, 0xffff0000, v187
	v_pk_fma_f32 v[40:41], v[170:171], v[34:35], v[32:33]
; DEV float fsilu(float x) { return x * fsigmoid(x); }
; DEV bf16x8 pack8(const float* x) { u32x4 o; o.x = pk2(x[0], x[1]); o.y = pk2(x[2], x[3]); o.z = pk2(x[4], x[5]); o.w = pk2(x[6], x[7]); return __builtin_bit_cast(bf16x8, o); }
; DEV void conv_silu8(const Fr& F, int seqrow0, int seqlen, int p, int zc, const float* cw, float scale, float* o) {
;     float a[8], x[8];
; #pragma unroll
;     for (int j = 0; j < 8; ++j) a[j] = 0.f;
; #pragma unroll
;     for (int tap = 0; tap < 3; ++tap) { const int pp = p + tap - 1; if (pp >= 0 && pp < seqlen) { unpack8(*(const u32x4*)(F.Z + (size_t)(seqrow0 + pp) * ZS + zc), x);
;         const f32x4 w0 = *(const f32x4*)(cw + tap * 512), w1 = *(const f32x4*)(cw + tap * 512 + 4);
; #pragma unroll
;         for (int j = 0; j < 4; ++j) { a[j] += x[j] * w0[j]; a[4 + j] += x[4 + j] * w1[j]; } } }
; #pragma unroll
;     for (int j = 0; j < 8; ++j) o[j] = fsilu(a[j]) * scale;
; }
; DEV void ml_local_item(const Fr& F, int l, int b, int ch, int h) {
;     ...
;     u32x4 vv[2]; float kk[2][8];
; #pragma unroll
;     for (int i = 0; i < 2; ++i) { const int idx = tid + NTHR * i; const int s = idx >> 3, c8 = (idx & 7) * 8;
;         vv[i] = *(const u32x4*)(F.Z + (size_t)(row0 + s) * ZS + ZC_MV + h * 64 + c8);
;         conv_silu8(F, seqrow0, seqlen, p0 + s, ZC_MK + h * 64 + c8, F.in[I_CONVW] + l * 1536 + 256 + h * 64 + c8, 0.125f, kk[i]);
;         *(bf16x8*)(F.A + (size_t)(row0 + s) * 256 + h * 64 + c8) = pack8(kk[i]); }
.LBB0_320:
	s_or_b64 exec, exec, s[6:7]
	s_mov_b64 s[6:7], 0x400
	v_add_u32_e32 v31, 2, v7
	v_lshl_add_u64 v[32:33], v[16:17], 0, s[6:7]
	v_cmp_lt_i32_e32 vcc, -2, v7
	v_cmp_ge_i32_e64 s[8:9], s27, v31
	s_mov_b64 s[6:7], 0x1000
	s_and_b64 s[8:9], vcc, s[8:9]
	v_lshl_add_u64 v[34:35], v[32:33], 0, s[6:7]
	s_and_saveexec_b64 s[6:7], s[8:9]
	s_cbranch_execz .LBB0_322
	v_lshlrev_b32_e32 v46, 16, v80
	v_and_b32_e32 v47, 0xffff0000, v80
	v_lshlrev_b32_e32 v42, 16, v81
	v_and_b32_e32 v43, 0xffff0000, v81
	v_pk_fma_f32 v[38:39], v[172:173], v[46:47], v[38:39]
	v_lshlrev_b32_e32 v46, 16, v82
	v_and_b32_e32 v47, 0xffff0000, v82
	v_pk_fma_f32 v[36:37], v[174:175], v[42:43], v[36:37]
	v_lshlrev_b32_e32 v42, 16, v83
	v_and_b32_e32 v43, 0xffff0000, v83
	v_pk_fma_f32 v[8:9], v[176:177], v[46:47], v[8:9]
	v_pk_fma_f32 v[40:41], v[178:179], v[42:43], v[40:41]
.LBB0_322:
	s_or_b64 exec, exec, s[6:7]
	v_mul_f32_e32 v7, 0xbfb8aa3b, v38
	v_exp_f32_e32 v7, v7
	v_mul_f32_e32 v31, 0xbfb8aa3b, v39
	v_exp_f32_e32 v31, v31
	s_lshl_b32 s60, s33, 1
	v_add_f32_e32 v7, 1.0, v7
	v_rcp_f32_e32 v42, v7
	v_add_f32_e32 v31, 1.0, v31
	v_rcp_f32_e32 v31, v31
	v_ashrrev_i32_e32 v7, 31, v6
	v_mul_f32_e32 v38, v38, v42
	v_mul_f32_e32 v56, 0x3e000000, v38
	v_mul_f32_e32 v31, v39, v31
	v_mul_f32_e32 v38, 0xbfb8aa3b, v36
	v_mul_f32_e32 v39, 0xbfb8aa3b, v37
	v_exp_f32_e32 v38, v38
	v_exp_f32_e32 v39, v39
	v_mul_f32_e32 v57, 0x3e000000, v31
	v_lshlrev_b64 v[6:7], 9, v[6:7]
	v_add_f32_e32 v31, 1.0, v38
	v_add_f32_e32 v38, 1.0, v39
	v_mul_f32_e32 v39, 0xbfb8aa3b, v8
	v_rcp_f32_e32 v31, v31
	v_exp_f32_e32 v39, v39
	v_rcp_f32_e32 v38, v38
	v_lshl_add_u64 v[6:7], s[12:13], 0, v[6:7]
	v_mul_f32_e32 v31, v36, v31
	v_add_f32_e32 v36, 1.0, v39
	v_mul_f32_e32 v58, 0x3e000000, v31
	v_mul_f32_e32 v31, v37, v38
	v_rcp_f32_e32 v36, v36
	v_mul_f32_e32 v37, 0xbfb8aa3b, v9
	v_exp_f32_e32 v37, v37
	v_mul_f32_e32 v59, 0x3e000000, v31
	v_mul_f32_e32 v8, v8, v36
	v_mul_f32_e32 v60, 0x3e000000, v8
	v_add_f32_e32 v8, 1.0, v37
	v_mul_f32_e32 v31, 0xbfb8aa3b, v40
	v_rcp_f32_e32 v8, v8
	v_exp_f32_e32 v31, v31
	v_mul_f32_e32 v36, 0xbfb8aa3b, v41
	v_exp_f32_e32 v36, v36
	v_mul_f32_e32 v8, v9, v8
	v_add_f32_e32 v9, 1.0, v31
	v_rcp_f32_e32 v9, v9
	v_add_f32_e32 v31, 1.0, v36
	v_rcp_f32_e32 v31, v31
	v_mul_f32_e32 v61, 0x3e000000, v8
	v_mul_f32_e32 v8, v40, v9
	v_mul_f32_e32 v62, 0x3e000000, v8
	v_mul_f32_e32 v8, v41, v31
	v_lshl_add_u64 v[6:7], v[6:7], 0, s[60:61]
	v_mov_b32_e32 v31, v0
	v_cvt_pk_bf16_f32 v36, v56, v57
	v_lshl_add_u64 v[6:7], v[6:7], 0, v[30:31]
	v_mul_f32_e32 v63, 0x3e000000, v8
	v_cvt_pk_bf16_f32 v37, v58, v59
	v_cvt_pk_bf16_f32 v38, v60, v61
	v_cvt_pk_bf16_f32 v39, v62, v63
	global_store_dwordx4 v[6:7], v[36:39], off
	v_mov_b64_e32 v[6:7], s[78:79]
	v_mov_b32_e32 v46, 0
	v_add_u32_e32 v36, s29, v49
	v_mad_i64_i32 v[6:7], s[6:7], v36, s53, v[6:7]
	v_lshl_add_u64 v[6:7], v[6:7], 0, s[60:61]
	v_lshl_add_u64 v[6:7], v[6:7], 0, v[30:31]
	global_load_dwordx4 v[6:9], v[6:7], off offset:2048
	v_add_u32_e32 v31, s31, v49
	v_cmp_lt_i32_e32 vcc, 0, v31
	v_cmp_ge_i32_e64 s[8:9], s27, v31
	s_and_b64 s[8:9], vcc, s[8:9]
	v_mov_b32_e32 v47, 0
	v_mov_b32_e32 v42, 0
	v_mov_b32_e32 v43, 0
	v_mov_b32_e32 v40, 0
	v_mov_b32_e32 v41, v46
	v_mov_b32_e32 v38, v46
	v_mov_b32_e32 v39, v46
	v_mov_b32_e32 v44, 0
	v_mov_b32_e32 v45, 0
	s_and_saveexec_b64 s[6:7], s[8:9]
	s_cbranch_execz .LBB0_324
	v_lshlrev_b32_e32 v42, 16, v84
	v_and_b32_e32 v43, 0xffff0000, v84
	v_lshlrev_b32_e32 v44, 16, v85
	v_and_b32_e32 v45, 0xffff0000, v85
	v_pk_fma_f32 v[40:41], v[158:159], v[44:45], 0 op_sel_hi:[1,1,0]
	v_lshlrev_b32_e32 v44, 16, v87
	v_and_b32_e32 v45, 0xffff0000, v87
	v_pk_fma_f32 v[42:43], v[156:157], v[42:43], 0 op_sel_hi:[1,1,0]
	v_lshlrev_b32_e32 v38, 16, v86
	v_and_b32_e32 v39, 0xffff0000, v86
	v_pk_fma_f32 v[46:47], v[162:163], v[44:45], 0 op_sel_hi:[1,1,0]
	v_pk_fma_f32 v[38:39], v[160:161], v[38:39], 0 op_sel_hi:[1,1,0]
	v_mov_b32_e32 v44, v46
	v_mov_b32_e32 v45, v47
.LBB0_324:
	s_or_b64 exec, exec, s[6:7]
	v_cmp_gt_u32_e32 vcc, s27, v31
	s_and_saveexec_b64 s[6:7], vcc
	s_cbranch_execz .LBB0_326
	v_lshlrev_b32_e32 v16, 16, v88
	v_and_b32_e32 v17, 0xffff0000, v88
	v_pk_fma_f32 v[42:43], v[164:165], v[16:17], v[42:43]
	v_lshlrev_b32_e32 v16, 16, v90
	v_and_b32_e32 v17, 0xffff0000, v90
	v_pk_fma_f32 v[38:39], v[168:169], v[16:17], v[38:39]
	v_lshlrev_b32_e32 v16, 16, v89
	v_and_b32_e32 v17, 0xffff0000, v89
	v_pk_fma_f32 v[40:41], v[166:167], v[16:17], v[40:41]
	v_lshlrev_b32_e32 v16, 16, v91
	v_and_b32_e32 v17, 0xffff0000, v91
	v_pk_fma_f32 v[44:45], v[170:171], v[16:17], v[46:47]
.LBB0_326:
	s_or_b64 exec, exec, s[6:7]
	v_add_u32_e32 v16, 2, v31
	v_cmp_lt_i32_e32 vcc, -2, v31
	v_cmp_ge_i32_e64 s[8:9], s27, v16
	s_and_b64 s[8:9], vcc, s[8:9]
	s_and_saveexec_b64 s[6:7], s[8:9]
	s_cbranch_execz .LBB0_328
	v_lshlrev_b32_e32 v46, 16, v92
	v_and_b32_e32 v47, 0xffff0000, v92
	v_lshlrev_b32_e32 v14, 16, v93
	v_and_b32_e32 v15, 0xffff0000, v93
	v_pk_fma_f32 v[42:43], v[172:173], v[46:47], v[42:43]
	v_lshlrev_b32_e32 v46, 16, v94
	v_and_b32_e32 v47, 0xffff0000, v94
	v_pk_fma_f32 v[40:41], v[174:175], v[14:15], v[40:41]
	v_lshlrev_b32_e32 v14, 16, v95
	v_and_b32_e32 v15, 0xffff0000, v95
	v_pk_fma_f32 v[38:39], v[176:177], v[46:47], v[38:39]
	v_pk_fma_f32 v[44:45], v[178:179], v[14:15], v[44:45]

; #define LAS __attribute__((address_space(3)))
; DEV void ml_local_item(const Fr& F, int l, int b, int ch, int h) {
;     ...
;     if (tid < 128) { const int dir = tid >> 6, d = tid & 63; const LAS bf16_t* KT = (dir ? KTb : KTf) + d; float s = 0.f;
;         for (int i = 0; i < 128; ++i) s += bf2f(KT[i * 72]);
;         const int chain = dir * 8 + b * 4 + h; F.NL[((size_t)chain * NCH + ch) * 64 + d] = s; }
.LBB0_334:
	v_add_u32_e32 v3, s7, v52
	ds_read_u16 v156, v3
	ds_read_u16 v157, v3 offset:144
	ds_read_u16 v158, v3 offset:288
	ds_read_u16 v159, v3 offset:432
	ds_read_u16 v160, v3 offset:576
	ds_read_u16 v161, v3 offset:720
	ds_read_u16 v162, v3 offset:864
	ds_read_u16 v163, v3 offset:1008
	ds_read_u16 v164, v3 offset:1152
	ds_read_u16 v165, v3 offset:1296
	ds_read_u16 v166, v3 offset:1440
	ds_read_u16 v167, v3 offset:1584
	ds_read_u16 v168, v3 offset:1728
	ds_read_u16 v169, v3 offset:1872
	ds_read_u16 v170, v3 offset:2016
	ds_read_u16 v171, v3 offset:2160
	s_addk_i32 s7, 0x900
	s_cmpk_eq_i32 s7, 0x4800
	s_waitcnt lgkmcnt(15)
	v_lshlrev_b32_e32 v156, 16, v156
	v_add_f32_e32 v2, v2, v156
	s_waitcnt lgkmcnt(14)
	v_lshlrev_b32_e32 v157, 16, v157
	v_add_f32_e32 v2, v2, v157
	s_waitcnt lgkmcnt(13)
	v_lshlrev_b32_e32 v158, 16, v158
	v_add_f32_e32 v2, v2, v158
	s_waitcnt lgkmcnt(12)
	v_lshlrev_b32_e32 v159, 16, v159
	v_add_f32_e32 v2, v2, v159
	s_waitcnt lgkmcnt(11)
	v_lshlrev_b32_e32 v160, 16, v160
	v_add_f32_e32 v2, v2, v160
	s_waitcnt lgkmcnt(10)
	v_lshlrev_b32_e32 v161, 16, v161
	v_add_f32_e32 v2, v2, v161
	s_waitcnt lgkmcnt(9)
	v_lshlrev_b32_e32 v162, 16, v162
	v_add_f32_e32 v2, v2, v162
	s_waitcnt lgkmcnt(8)
	v_lshlrev_b32_e32 v163, 16, v163
	v_add_f32_e32 v2, v2, v163
	s_waitcnt lgkmcnt(7)
	v_lshlrev_b32_e32 v164, 16, v164
	v_add_f32_e32 v2, v2, v164
	s_waitcnt lgkmcnt(6)
	v_lshlrev_b32_e32 v165, 16, v165
	v_add_f32_e32 v2, v2, v165
	s_waitcnt lgkmcnt(5)
	v_lshlrev_b32_e32 v166, 16, v166
	v_add_f32_e32 v2, v2, v166
	s_waitcnt lgkmcnt(4)
	v_lshlrev_b32_e32 v167, 16, v167
	v_add_f32_e32 v2, v2, v167
	s_waitcnt lgkmcnt(3)
	v_lshlrev_b32_e32 v168, 16, v168
	v_add_f32_e32 v2, v2, v168
	s_waitcnt lgkmcnt(2)
	v_lshlrev_b32_e32 v169, 16, v169
	v_add_f32_e32 v2, v2, v169
	s_waitcnt lgkmcnt(1)
	v_lshlrev_b32_e32 v170, 16, v170
	v_add_f32_e32 v2, v2, v170
	s_waitcnt lgkmcnt(0)
	v_lshlrev_b32_e32 v171, 16, v171
	v_add_f32_e32 v2, v2, v171
	s_cbranch_scc0 .LBB0_334
	v_add_u32_e32 v3, s6, v53
	v_or_b32_e32 v3, s26, v3
	v_mov_b64_e32 v[4:5], s[18:19]
	s_movk_i32 s6, 0x82
	v_mad_i64_i32 v[4:5], s[6:7], v3, s6, v[4:5]
	v_lshlrev_b64 v[4:5], 8, v[4:5]
	v_lshl_add_u64 v[4:5], v[28:29], 0, v[4:5]
	global_store_dword v[4:5], v2, off
	s_branch .LBB0_313

; #define LAS __attribute__((address_space(3)))
; DEV void attn_item(const Fr& F, int l, int b, int qb, int kvh, bool ctxq) {
;     ...
;         const int nlo = (kt == 2) ? 2 * rq : 0, nhi = (kt == 4) ? 2 * rq + 2 : 8;
;         f32x4 sc[2][8];
; #pragma unroll
;         for (int nt = 0; nt < 8; ++nt) { if (nt >= nlo && nt < nhi) {
;             const bf16x8 y0 = *(const LAS bf16x8*)(Ks + (nt * 16 + fr) * 72 + 8 * fq), y1 = *(const LAS bf16x8*)(Ks + (nt * 16 + fr) * 72 + 32 + 8 * fq);
; #pragma unroll
;             for (int mt = 0; mt < 2; ++mt) { f32x4 a = __builtin_amdgcn_mfma_f32_16x16x32_bf16(y0, xq[mt][0], (f32x4){0.f, 0.f, 0.f, 0.f}, 0, 0, 0);
;                 sc[mt][nt] = __builtin_amdgcn_mfma_f32_16x16x32_bf16(y1, xq[mt][1], a, 0, 0, 0); } }
;             else { sc[0][nt] = (f32x4){0.f, 0.f, 0.f, 0.f}; sc[1][nt] = sc[0][nt]; } }
;         float scl[2];
; #pragma unroll
;         for (int mt = 0; mt < 2; ++mt) {
;             const int tl = r0 + mt * 16 + fr;
;             float mx = -INFINITY;
; #pragma unroll
;             for (int nt = 0; nt < 8; ++nt) { if (nt >= nlo && nt < nhi) {
;                 const bool dg = (kt == 2 || kt == 4) && (nt == 2 * rq + mt);
;                 if (dg) {
; #pragma unroll
;                     for (int j = 0; j < 4; ++j) { const int si = nt * 16 + 4 * fq + j; const bool ok = (kt == 2) ? (si >= tl) : (si <= tl); sc[mt][nt][j] = ok ? sc[mt][nt][j] : -INFINITY; } }
;                 else if ((kt == 2 && nt < 2 * rq + mt) || (kt == 4 && nt > 2 * rq + mt)) sc[mt][nt] = (f32x4){-INFINITY, -INFINITY, -INFINITY, -INFINITY};
;                 mx = fmaxf(fmaxf(mx, fmaxf(sc[mt][nt][0], sc[mt][nt][1])), fmaxf(sc[mt][nt][2], sc[mt][nt][3])); } }
.LBB0_511:
	ds_read_b128 v[244:247], v163
	ds_read_b128 v[248:251], v163 offset:64
	ds_read_b128 v[252:255], v163 offset:2304
	ds_read_b128 v[216:219], v163 offset:2368
	s_waitcnt lgkmcnt(2)
	v_mfma_f32_16x16x32_bf16 v[76:79], v[244:247], v[4:7], 0
	v_mfma_f32_16x16x32_bf16 v[108:111], v[244:247], v[36:39], 0
	v_mfma_f32_16x16x32_bf16 v[76:79], v[248:251], v[8:11], v[76:79]
	v_mfma_f32_16x16x32_bf16 v[108:111], v[248:251], v[72:75], v[108:111]
	ds_read_b128 v[244:247], v163 offset:4608
	ds_read_b128 v[248:251], v163 offset:4672
	s_waitcnt lgkmcnt(2)
	v_mfma_f32_16x16x32_bf16 v[80:83], v[252:255], v[4:7], 0
	v_mfma_f32_16x16x32_bf16 v[112:115], v[252:255], v[36:39], 0
	v_mfma_f32_16x16x32_bf16 v[80:83], v[216:219], v[8:11], v[80:83]
	v_mfma_f32_16x16x32_bf16 v[112:115], v[216:219], v[72:75], v[112:115]
	ds_read_b128 v[252:255], v163 offset:6912
	ds_read_b128 v[216:219], v163 offset:6976
	s_waitcnt lgkmcnt(2)
	v_mfma_f32_16x16x32_bf16 v[84:87], v[244:247], v[4:7], 0
	v_mfma_f32_16x16x32_bf16 v[116:119], v[244:247], v[36:39], 0
	v_mfma_f32_16x16x32_bf16 v[84:87], v[248:251], v[8:11], v[84:87]
	v_mfma_f32_16x16x32_bf16 v[116:119], v[248:251], v[72:75], v[116:119]
	ds_read_b128 v[244:247], v163 offset:9216
	ds_read_b128 v[248:251], v163 offset:9280
	s_waitcnt lgkmcnt(2)
	v_mfma_f32_16x16x32_bf16 v[88:91], v[252:255], v[4:7], 0
	v_mfma_f32_16x16x32_bf16 v[120:123], v[252:255], v[36:39], 0
	v_mfma_f32_16x16x32_bf16 v[88:91], v[216:219], v[8:11], v[88:91]
	v_mfma_f32_16x16x32_bf16 v[120:123], v[216:219], v[72:75], v[120:123]
	ds_read_b128 v[252:255], v163 offset:11520
	ds_read_b128 v[216:219], v163 offset:11584
	s_waitcnt lgkmcnt(2)
	v_mfma_f32_16x16x32_bf16 v[92:95], v[244:247], v[4:7], 0
	v_mfma_f32_16x16x32_bf16 v[124:127], v[244:247], v[36:39], 0
	v_mfma_f32_16x16x32_bf16 v[92:95], v[248:251], v[8:11], v[92:95]
	v_mfma_f32_16x16x32_bf16 v[124:127], v[248:251], v[72:75], v[124:127]
	ds_read_b128 v[244:247], v163 offset:13824
	ds_read_b128 v[248:251], v163 offset:13888
	s_waitcnt lgkmcnt(2)
	v_mfma_f32_16x16x32_bf16 v[96:99], v[252:255], v[4:7], 0
	v_mfma_f32_16x16x32_bf16 v[128:131], v[252:255], v[36:39], 0
	v_mfma_f32_16x16x32_bf16 v[96:99], v[216:219], v[8:11], v[96:99]
	v_mfma_f32_16x16x32_bf16 v[128:131], v[216:219], v[72:75], v[128:131]
	ds_read_b128 v[252:255], v163 offset:16128
	ds_read_b128 v[216:219], v163 offset:16192
	s_waitcnt lgkmcnt(2)
	v_mfma_f32_16x16x32_bf16 v[100:103], v[244:247], v[4:7], 0
	v_mfma_f32_16x16x32_bf16 v[132:135], v[244:247], v[36:39], 0
	v_mfma_f32_16x16x32_bf16 v[100:103], v[248:251], v[8:11], v[100:103]
	v_mfma_f32_16x16x32_bf16 v[132:135], v[248:251], v[72:75], v[132:135]
	s_waitcnt lgkmcnt(0)
	v_mfma_f32_16x16x32_bf16 v[104:107], v[252:255], v[4:7], 0
	v_mfma_f32_16x16x32_bf16 v[136:139], v[252:255], v[36:39], 0
	v_mfma_f32_16x16x32_bf16 v[104:107], v[216:219], v[8:11], v[104:107]
	v_mfma_f32_16x16x32_bf16 v[136:139], v[216:219], v[72:75], v[136:139]
	v_and_b32_e32 v252, 63, v188
	v_lshrrev_b32_e32 v253, 6, v188
	v_and_b32_e32 v254, 15, v252
	v_lshrrev_b32_e32 v255, 4, v252
	v_xor_b32_e32 v245, 16, v252
	v_xor_b32_e32 v246, 32, v252
	v_lshlrev_b32_e32 v245, 2, v245
	v_lshlrev_b32_e32 v246, 2, v246
	v_and_b32_e32 v244, 3, v253
	v_lshlrev_b32_e32 v244, 5, v244
	v_add_u32_e32 v244, v244, v254
	v_lshlrev_b32_e32 v251, 2, v255
	v_sub_u32_e32 v244, v244, v251
	v_mul_u32_u24_e32 v247, 0x2200, v253
	v_mul_u32_u24_e32 v251, 0x110, v254
	v_add_u32_e32 v247, v247, v251
	v_lshl_add_u32 v248, v255, 4, v247
	v_lshl_add_u32 v247, v255, 3, v247
	v_mul_u32_u24_e32 v249, 0x480, v255
	v_lshrrev_b32_e32 v251, 2, v254
	v_mul_u32_u24_e32 v251, 0x90, v251
	v_add_u32_e32 v249, v249, v251
	v_and_b32_e32 v251, 3, v254
	v_lshl_add_u32 v249, v251, 3, v249
	v_mov_b32_e32 v250, 0xff800000
	s_nop 7
	s_cmp_eq_u32 s65, 2
	s_cbranch_scc1 .Latt_mask_prev
	s_cmp_eq_u32 s65, 4
	s_cbranch_scc1 .Latt_mask_next
	s_branch .Latt_mask_done
.Latt_mask_prev:
	v_subrev_u32_e32 v251, 0, v244
	v_cmp_ge_i32_e64 s[80:81], 0, v251
	v_cmp_ge_i32_e64 s[82:83], 1, v251
	v_cmp_ge_i32_e64 s[84:85], 2, v251
	v_cmp_ge_i32_e64 s[86:87], 3, v251
	v_cndmask_b32_e64 v76, v250, v76, s[80:81]
	v_cndmask_b32_e64 v77, v250, v77, s[82:83]
	v_cndmask_b32_e64 v78, v250, v78, s[84:85]
	v_cndmask_b32_e64 v79, v250, v79, s[86:87]
	v_subrev_u32_e32 v251, 16, v244
	v_cmp_ge_i32_e64 s[80:81], 0, v251
	v_cmp_ge_i32_e64 s[82:83], 1, v251
	v_cmp_ge_i32_e64 s[84:85], 2, v251
	v_cmp_ge_i32_e64 s[86:87], 3, v251
	v_cndmask_b32_e64 v80, v250, v80, s[80:81]
	v_cndmask_b32_e64 v81, v250, v81, s[82:83]
	v_cndmask_b32_e64 v82, v250, v82, s[84:85]
	v_cndmask_b32_e64 v83, v250, v83, s[86:87]
	v_subrev_u32_e32 v251, 32, v244
	v_cmp_ge_i32_e64 s[80:81], 0, v251
	v_cmp_ge_i32_e64 s[82:83], 1, v251
	v_cmp_ge_i32_e64 s[84:85], 2, v251
	v_cmp_ge_i32_e64 s[86:87], 3, v251
	v_cndmask_b32_e64 v84, v250, v84, s[80:81]
	v_cndmask_b32_e64 v85, v250, v85, s[82:83]
	v_cndmask_b32_e64 v86, v250, v86, s[84:85]
	v_cndmask_b32_e64 v87, v250, v87, s[86:87]
	v_subrev_u32_e32 v251, 48, v244
	v_cmp_ge_i32_e64 s[80:81], 0, v251
	v_cmp_ge_i32_e64 s[82:83], 1, v251
	v_cmp_ge_i32_e64 s[84:85], 2, v251
	v_cmp_ge_i32_e64 s[86:87], 3, v251
	v_cndmask_b32_e64 v88, v250, v88, s[80:81]
	v_cndmask_b32_e64 v89, v250, v89, s[82:83]
	v_cndmask_b32_e64 v90, v250, v90, s[84:85]
	v_cndmask_b32_e64 v91, v250, v91, s[86:87]
	v_subrev_u32_e32 v251, 64, v244
	v_cmp_ge_i32_e64 s[80:81], 0, v251
	v_cmp_ge_i32_e64 s[82:83], 1, v251
	v_cmp_ge_i32_e64 s[84:85], 2, v251
	v_cmp_ge_i32_e64 s[86:87], 3, v251
	v_cndmask_b32_e64 v92, v250, v92, s[80:81]
	v_cndmask_b32_e64 v93, v250, v93, s[82:83]
	v_cndmask_b32_e64 v94, v250, v94, s[84:85]
; DEV void attn_item(const Fr& F, int l, int b, int qb, int kvh, bool ctxq) {
;     ...
;             for (int nt = 0; nt < 8; ++nt) { if (nt >= nlo && nt < nhi) {
;                 const bool dg = (kt == 2 || kt == 4) && (nt == 2 * rq + mt);
;                 if (dg) {
; #pragma unroll
;                     for (int j = 0; j < 4; ++j) { const int si = nt * 16 + 4 * fq + j; const bool ok = (kt == 2) ? (si >= tl) : (si <= tl); sc[mt][nt][j] = ok ? sc[mt][nt][j] : -INFINITY; } }
;                 else if ((kt == 2 && nt < 2 * rq + mt) || (kt == 4 && nt > 2 * rq + mt)) sc[mt][nt] = (f32x4){-INFINITY, -INFINITY, -INFINITY, -INFINITY};
;                 mx = fmaxf(fmaxf(mx, fmaxf(sc[mt][nt][0], sc[mt][nt][1])), fmaxf(sc[mt][nt][2], sc[mt][nt][3])); } }
	v_cndmask_b32_e64 v95, v250, v95, s[86:87]
	v_subrev_u32_e32 v251, 80, v244
	v_cmp_ge_i32_e64 s[80:81], 0, v251
	v_cmp_ge_i32_e64 s[82:83], 1, v251
	v_cmp_ge_i32_e64 s[84:85], 2, v251
	v_cmp_ge_i32_e64 s[86:87], 3, v251
	v_cndmask_b32_e64 v96, v250, v96, s[80:81]
	v_cndmask_b32_e64 v97, v250, v97, s[82:83]
	v_cndmask_b32_e64 v98, v250, v98, s[84:85]
	v_cndmask_b32_e64 v99, v250, v99, s[86:87]
	v_subrev_u32_e32 v251, 96, v244
	v_cmp_ge_i32_e64 s[80:81], 0, v251
	v_cmp_ge_i32_e64 s[82:83], 1, v251
	v_cmp_ge_i32_e64 s[84:85], 2, v251
	v_cmp_ge_i32_e64 s[86:87], 3, v251
	v_cndmask_b32_e64 v100, v250, v100, s[80:81]
	v_cndmask_b32_e64 v101, v250, v101, s[82:83]
	v_cndmask_b32_e64 v102, v250, v102, s[84:85]
	v_cndmask_b32_e64 v103, v250, v103, s[86:87]
	v_subrev_u32_e32 v251, 112, v244
	v_cmp_ge_i32_e64 s[80:81], 0, v251
	v_cmp_ge_i32_e64 s[82:83], 1, v251
	v_cmp_ge_i32_e64 s[84:85], 2, v251
	v_cmp_ge_i32_e64 s[86:87], 3, v251
	v_cndmask_b32_e64 v104, v250, v104, s[80:81]
	v_cndmask_b32_e64 v105, v250, v105, s[82:83]
	v_cndmask_b32_e64 v106, v250, v106, s[84:85]
	v_cndmask_b32_e64 v107, v250, v107, s[86:87]
	v_add_u32_e32 v251, 16, v244
	v_cmp_ge_i32_e64 s[80:81], 0, v251
	v_cmp_ge_i32_e64 s[82:83], 1, v251
	v_cmp_ge_i32_e64 s[84:85], 2, v251
	v_cmp_ge_i32_e64 s[86:87], 3, v251
	v_cndmask_b32_e64 v108, v250, v108, s[80:81]
	v_cndmask_b32_e64 v109, v250, v109, s[82:83]
	v_cndmask_b32_e64 v110, v250, v110, s[84:85]
	v_cndmask_b32_e64 v111, v250, v111, s[86:87]
	v_subrev_u32_e32 v251, 0, v244
	v_cmp_ge_i32_e64 s[80:81], 0, v251
	v_cmp_ge_i32_e64 s[82:83], 1, v251
	v_cmp_ge_i32_e64 s[84:85], 2, v251
	v_cmp_ge_i32_e64 s[86:87], 3, v251
	v_cndmask_b32_e64 v112, v250, v112, s[80:81]
	v_cndmask_b32_e64 v113, v250, v113, s[82:83]
	v_cndmask_b32_e64 v114, v250, v114, s[84:85]
	v_cndmask_b32_e64 v115, v250, v115, s[86:87]
	v_subrev_u32_e32 v251, 16, v244
	v_cmp_ge_i32_e64 s[80:81], 0, v251
	v_cmp_ge_i32_e64 s[82:83], 1, v251
	v_cmp_ge_i32_e64 s[84:85], 2, v251
	v_cmp_ge_i32_e64 s[86:87], 3, v251
	v_cndmask_b32_e64 v116, v250, v116, s[80:81]
	v_cndmask_b32_e64 v117, v250, v117, s[82:83]
	v_cndmask_b32_e64 v118, v250, v118, s[84:85]
	v_cndmask_b32_e64 v119, v250, v119, s[86:87]
	v_subrev_u32_e32 v251, 32, v244
	v_cmp_ge_i32_e64 s[80:81], 0, v251
	v_cmp_ge_i32_e64 s[82:83], 1, v251
	v_cmp_ge_i32_e64 s[84:85], 2, v251
	v_cmp_ge_i32_e64 s[86:87], 3, v251
	v_cndmask_b32_e64 v120, v250, v120, s[80:81]
	v_cndmask_b32_e64 v121, v250, v121, s[82:83]
	v_cndmask_b32_e64 v122, v250, v122, s[84:85]
	v_cndmask_b32_e64 v123, v250, v123, s[86:87]
	v_subrev_u32_e32 v251, 48, v244
	v_cmp_ge_i32_e64 s[80:81], 0, v251
	v_cmp_ge_i32_e64 s[82:83], 1, v251
	v_cmp_ge_i32_e64 s[84:85], 2, v251
	v_cmp_ge_i32_e64 s[86:87], 3, v251
	v_cndmask_b32_e64 v124, v250, v124, s[80:81]
	v_cndmask_b32_e64 v125, v250, v125, s[82:83]
	v_cndmask_b32_e64 v126, v250, v126, s[84:85]
	v_cndmask_b32_e64 v127, v250, v127, s[86:87]
	v_subrev_u32_e32 v251, 64, v244
	v_cmp_ge_i32_e64 s[80:81], 0, v251
	v_cmp_ge_i32_e64 s[82:83], 1, v251
	v_cmp_ge_i32_e64 s[84:85], 2, v251
	v_cmp_ge_i32_e64 s[86:87], 3, v251
	v_cndmask_b32_e64 v128, v250, v128, s[80:81]
	v_cndmask_b32_e64 v129, v250, v129, s[82:83]
	v_cndmask_b32_e64 v130, v250, v130, s[84:85]
	v_cndmask_b32_e64 v131, v250, v131, s[86:87]
	v_subrev_u32_e32 v251, 80, v244
	v_cmp_ge_i32_e64 s[80:81], 0, v251
	v_cmp_ge_i32_e64 s[82:83], 1, v251
	v_cmp_ge_i32_e64 s[84:85], 2, v251
	v_cmp_ge_i32_e64 s[86:87], 3, v251
	v_cndmask_b32_e64 v132, v250, v132, s[80:81]
	v_cndmask_b32_e64 v133, v250, v133, s[82:83]
	v_cndmask_b32_e64 v134, v250, v134, s[84:85]
	v_cndmask_b32_e64 v135, v250, v135, s[86:87]
	v_subrev_u32_e32 v251, 96, v244
	v_cmp_ge_i32_e64 s[80:81], 0, v251
	v_cmp_ge_i32_e64 s[82:83], 1, v251
	v_cmp_ge_i32_e64 s[84:85], 2, v251
	v_cmp_ge_i32_e64 s[86:87], 3, v251
	v_cndmask_b32_e64 v136, v250, v136, s[80:81]
	v_cndmask_b32_e64 v137, v250, v137, s[82:83]
	v_cndmask_b32_e64 v138, v250, v138, s[84:85]
	v_cndmask_b32_e64 v139, v250, v139, s[86:87]
	s_branch .Latt_mask_done
.Latt_mask_next:
	v_subrev_u32_e32 v251, 0, v244
	v_cmp_le_i32_e64 s[80:81], 0, v251
	v_cmp_le_i32_e64 s[82:83], 1, v251
	v_cmp_le_i32_e64 s[84:85], 2, v251
	v_cmp_le_i32_e64 s[86:87], 3, v251
	v_cndmask_b32_e64 v76, v250, v76, s[80:81]
	v_cndmask_b32_e64 v77, v250, v77, s[82:83]
	v_cndmask_b32_e64 v78, v250, v78, s[84:85]
	v_cndmask_b32_e64 v79, v250, v79, s[86:87]
	v_subrev_u32_e32 v251, 16, v244
	v_cmp_le_i32_e64 s[80:81], 0, v251
	v_cmp_le_i32_e64 s[82:83], 1, v251
	v_cmp_le_i32_e64 s[84:85], 2, v251
	v_cmp_le_i32_e64 s[86:87], 3, v251
	v_cndmask_b32_e64 v80, v250, v80, s[80:81]
	v_cndmask_b32_e64 v81, v250, v81, s[82:83]
	v_cndmask_b32_e64 v82, v250, v82, s[84:85]
	v_cndmask_b32_e64 v83, v250, v83, s[86:87]
	v_subrev_u32_e32 v251, 32, v244
	v_cmp_le_i32_e64 s[80:81], 0, v251
	v_cmp_le_i32_e64 s[82:83], 1, v251
	v_cmp_le_i32_e64 s[84:85], 2, v251
	v_cmp_le_i32_e64 s[86:87], 3, v251
	v_cndmask_b32_e64 v84, v250, v84, s[80:81]
	v_cndmask_b32_e64 v85, v250, v85, s[82:83]
	v_cndmask_b32_e64 v86, v250, v86, s[84:85]
	v_cndmask_b32_e64 v87, v250, v87, s[86:87]
	v_subrev_u32_e32 v251, 48, v244
	v_cmp_le_i32_e64 s[80:81], 0, v251
	v_cmp_le_i32_e64 s[82:83], 1, v251
	v_cmp_le_i32_e64 s[84:85], 2, v251
	v_cmp_le_i32_e64 s[86:87], 3, v251
	v_cndmask_b32_e64 v88, v250, v88, s[80:81]
	v_cndmask_b32_e64 v89, v250, v89, s[82:83]
	v_cndmask_b32_e64 v90, v250, v90, s[84:85]
	v_cndmask_b32_e64 v91, v250, v91, s[86:87]
	v_subrev_u32_e32 v251, 64, v244
	v_cmp_le_i32_e64 s[80:81], 0, v251
	v_cmp_le_i32_e64 s[82:83], 1, v251
	v_cmp_le_i32_e64 s[84:85], 2, v251
	v_cmp_le_i32_e64 s[86:87], 3, v251
; DEV void attn_item(const Fr& F, int l, int b, int qb, int kvh, bool ctxq) {
;     ...
;             for (int nt = 0; nt < 8; ++nt) { if (nt >= nlo && nt < nhi) {
;                 const bool dg = (kt == 2 || kt == 4) && (nt == 2 * rq + mt);
;                 if (dg) {
; #pragma unroll
;                     for (int j = 0; j < 4; ++j) { const int si = nt * 16 + 4 * fq + j; const bool ok = (kt == 2) ? (si >= tl) : (si <= tl); sc[mt][nt][j] = ok ? sc[mt][nt][j] : -INFINITY; } }
;                 else if ((kt == 2 && nt < 2 * rq + mt) || (kt == 4 && nt > 2 * rq + mt)) sc[mt][nt] = (f32x4){-INFINITY, -INFINITY, -INFINITY, -INFINITY};
;                 mx = fmaxf(fmaxf(mx, fmaxf(sc[mt][nt][0], sc[mt][nt][1])), fmaxf(sc[mt][nt][2], sc[mt][nt][3])); } }
;             mx = fmaxf(mx, __shfl_xor(mx, 16)); mx = fmaxf(mx, __shfl_xor(mx, 32));
	v_cndmask_b32_e64 v92, v250, v92, s[80:81]
	v_cndmask_b32_e64 v93, v250, v93, s[82:83]
	v_cndmask_b32_e64 v94, v250, v94, s[84:85]
	v_cndmask_b32_e64 v95, v250, v95, s[86:87]
	v_subrev_u32_e32 v251, 80, v244
	v_cmp_le_i32_e64 s[80:81], 0, v251
	v_cmp_le_i32_e64 s[82:83], 1, v251
	v_cmp_le_i32_e64 s[84:85], 2, v251
	v_cmp_le_i32_e64 s[86:87], 3, v251
	v_cndmask_b32_e64 v96, v250, v96, s[80:81]
	v_cndmask_b32_e64 v97, v250, v97, s[82:83]
	v_cndmask_b32_e64 v98, v250, v98, s[84:85]
	v_cndmask_b32_e64 v99, v250, v99, s[86:87]
	v_subrev_u32_e32 v251, 96, v244
	v_cmp_le_i32_e64 s[80:81], 0, v251
	v_cmp_le_i32_e64 s[82:83], 1, v251
	v_cmp_le_i32_e64 s[84:85], 2, v251
	v_cmp_le_i32_e64 s[86:87], 3, v251
	v_cndmask_b32_e64 v100, v250, v100, s[80:81]
	v_cndmask_b32_e64 v101, v250, v101, s[82:83]
	v_cndmask_b32_e64 v102, v250, v102, s[84:85]
	v_cndmask_b32_e64 v103, v250, v103, s[86:87]
	v_subrev_u32_e32 v251, 112, v244
	v_cmp_le_i32_e64 s[80:81], 0, v251
	v_cmp_le_i32_e64 s[82:83], 1, v251
	v_cmp_le_i32_e64 s[84:85], 2, v251
	v_cmp_le_i32_e64 s[86:87], 3, v251
	v_cndmask_b32_e64 v104, v250, v104, s[80:81]
	v_cndmask_b32_e64 v105, v250, v105, s[82:83]
	v_cndmask_b32_e64 v106, v250, v106, s[84:85]
	v_cndmask_b32_e64 v107, v250, v107, s[86:87]
	v_add_u32_e32 v251, 16, v244
	v_cmp_le_i32_e64 s[80:81], 0, v251
	v_cmp_le_i32_e64 s[82:83], 1, v251
	v_cmp_le_i32_e64 s[84:85], 2, v251
	v_cmp_le_i32_e64 s[86:87], 3, v251
	v_cndmask_b32_e64 v108, v250, v108, s[80:81]
	v_cndmask_b32_e64 v109, v250, v109, s[82:83]
	v_cndmask_b32_e64 v110, v250, v110, s[84:85]
	v_cndmask_b32_e64 v111, v250, v111, s[86:87]
	v_subrev_u32_e32 v251, 0, v244
	v_cmp_le_i32_e64 s[80:81], 0, v251
	v_cmp_le_i32_e64 s[82:83], 1, v251
	v_cmp_le_i32_e64 s[84:85], 2, v251
	v_cmp_le_i32_e64 s[86:87], 3, v251
	v_cndmask_b32_e64 v112, v250, v112, s[80:81]
	v_cndmask_b32_e64 v113, v250, v113, s[82:83]
	v_cndmask_b32_e64 v114, v250, v114, s[84:85]
	v_cndmask_b32_e64 v115, v250, v115, s[86:87]
	v_subrev_u32_e32 v251, 16, v244
	v_cmp_le_i32_e64 s[80:81], 0, v251
	v_cmp_le_i32_e64 s[82:83], 1, v251
	v_cmp_le_i32_e64 s[84:85], 2, v251
	v_cmp_le_i32_e64 s[86:87], 3, v251
	v_cndmask_b32_e64 v116, v250, v116, s[80:81]
	v_cndmask_b32_e64 v117, v250, v117, s[82:83]
	v_cndmask_b32_e64 v118, v250, v118, s[84:85]
	v_cndmask_b32_e64 v119, v250, v119, s[86:87]
	v_subrev_u32_e32 v251, 32, v244
	v_cmp_le_i32_e64 s[80:81], 0, v251
	v_cmp_le_i32_e64 s[82:83], 1, v251
	v_cmp_le_i32_e64 s[84:85], 2, v251
	v_cmp_le_i32_e64 s[86:87], 3, v251
	v_cndmask_b32_e64 v120, v250, v120, s[80:81]
	v_cndmask_b32_e64 v121, v250, v121, s[82:83]
	v_cndmask_b32_e64 v122, v250, v122, s[84:85]
	v_cndmask_b32_e64 v123, v250, v123, s[86:87]
	v_subrev_u32_e32 v251, 48, v244
	v_cmp_le_i32_e64 s[80:81], 0, v251
	v_cmp_le_i32_e64 s[82:83], 1, v251
	v_cmp_le_i32_e64 s[84:85], 2, v251
	v_cmp_le_i32_e64 s[86:87], 3, v251
	v_cndmask_b32_e64 v124, v250, v124, s[80:81]
	v_cndmask_b32_e64 v125, v250, v125, s[82:83]
	v_cndmask_b32_e64 v126, v250, v126, s[84:85]
	v_cndmask_b32_e64 v127, v250, v127, s[86:87]
	v_subrev_u32_e32 v251, 64, v244
	v_cmp_le_i32_e64 s[80:81], 0, v251
	v_cmp_le_i32_e64 s[82:83], 1, v251
	v_cmp_le_i32_e64 s[84:85], 2, v251
	v_cmp_le_i32_e64 s[86:87], 3, v251
	v_cndmask_b32_e64 v128, v250, v128, s[80:81]
	v_cndmask_b32_e64 v129, v250, v129, s[82:83]
	v_cndmask_b32_e64 v130, v250, v130, s[84:85]
	v_cndmask_b32_e64 v131, v250, v131, s[86:87]
	v_subrev_u32_e32 v251, 80, v244
	v_cmp_le_i32_e64 s[80:81], 0, v251
	v_cmp_le_i32_e64 s[82:83], 1, v251
	v_cmp_le_i32_e64 s[84:85], 2, v251
	v_cmp_le_i32_e64 s[86:87], 3, v251
	v_cndmask_b32_e64 v132, v250, v132, s[80:81]
	v_cndmask_b32_e64 v133, v250, v133, s[82:83]
	v_cndmask_b32_e64 v134, v250, v134, s[84:85]
	v_cndmask_b32_e64 v135, v250, v135, s[86:87]
	v_subrev_u32_e32 v251, 96, v244
	v_cmp_le_i32_e64 s[80:81], 0, v251
	v_cmp_le_i32_e64 s[82:83], 1, v251
	v_cmp_le_i32_e64 s[84:85], 2, v251
	v_cmp_le_i32_e64 s[86:87], 3, v251
	v_cndmask_b32_e64 v136, v250, v136, s[80:81]
	v_cndmask_b32_e64 v137, v250, v137, s[82:83]
	v_cndmask_b32_e64 v138, v250, v138, s[84:85]
	v_cndmask_b32_e64 v139, v250, v139, s[86:87]
.Latt_mask_done:
	v_max3_f32 v216, v76, v77, v78
	v_max3_f32 v216, v216, v79, v80
	v_max3_f32 v216, v216, v81, v82
	v_max3_f32 v216, v216, v83, v84
	v_max3_f32 v216, v216, v85, v86
	v_max3_f32 v216, v216, v87, v88
	v_max3_f32 v216, v216, v89, v90
	v_max3_f32 v216, v216, v91, v92
	v_max3_f32 v216, v216, v93, v94
	v_max3_f32 v216, v216, v95, v96
	v_max3_f32 v216, v216, v97, v98
	v_max3_f32 v216, v216, v99, v100
	v_max3_f32 v216, v216, v101, v102
	v_max3_f32 v216, v216, v103, v104
	v_max3_f32 v216, v216, v105, v106
	v_max_f32_e32 v216, v216, v107
	v_max3_f32 v217, v108, v109, v110
	v_max3_f32 v217, v217, v111, v112
	v_max3_f32 v217, v217, v113, v114
	v_max3_f32 v217, v217, v115, v116
	v_max3_f32 v217, v217, v117, v118
	v_max3_f32 v217, v217, v119, v120
	v_max3_f32 v217, v217, v121, v122
	v_max3_f32 v217, v217, v123, v124
	v_max3_f32 v217, v217, v125, v126
	v_max3_f32 v217, v217, v127, v128
	v_max3_f32 v217, v217, v129, v130
	v_max3_f32 v217, v217, v131, v132
	v_max3_f32 v217, v217, v133, v134
	v_max3_f32 v217, v217, v135, v136
	v_max3_f32 v217, v217, v137, v138
	v_max_f32_e32 v217, v217, v139
	ds_bpermute_b32 v252, v245, v216
	ds_bpermute_b32 v253, v245, v217
	s_waitcnt lgkmcnt(0)
	v_max_f32_e32 v216, v216, v252
	v_max_f32_e32 v217, v217, v253
	ds_bpermute_b32 v252, v246, v216
	ds_bpermute_b32 v253, v246, v217
	s_waitcnt lgkmcnt(0)
; #define LAS __attribute__((address_space(3)))
; DEV unsigned pk2(float lo, float hi) { unsigned r; asm("v_cvt_pk_bf16_f32 %0, %1, %2" : "=v"(r) : "v"(lo), "v"(hi)); return r; }
; DEV void attn_item(const Fr& F, int l, int b, int qb, int kvh, bool ctxq) {
;     ...
;             const float mn = fmaxf(mrow[mt], mx); scl[mt] = __builtin_amdgcn_exp2f(mrow[mt] - mn);
;             float sum = 0.f;
; #pragma unroll
;             for (int nt = 0; nt < 8; ++nt) { if (nt >= nlo && nt < nhi) { float p[4];
; #pragma unroll
;                 for (int j = 0; j < 4; ++j) { p[j] = __builtin_amdgcn_exp2f(sc[mt][nt][j] - mn); sum += p[j]; }
;                 u32x2 pw; pw.x = pk2(p[0], p[1]); pw.y = pk2(p[2], p[3]); *(LAS u32x2*)(Pw + (mt * 16 + fr) * 136 + nt * 16 + 4 * fq) = pw; } }
;             sum += __shfl_xor(sum, 16); sum += __shfl_xor(sum, 32);
;             lrow[mt] = lrow[mt] * scl[mt] + sum; mrow[mt] = mn;
; #pragma unroll
;             for (int n2 = 0; n2 < 4; ++n2) O[mt][n2] *= scl[mt];
	v_max3_f32 v1, v177, v216, v252
	v_max3_f32 v215, v175, v217, v253
	v_sub_f32_e32 v2, v177, v1
	v_sub_f32_e32 v243, v175, v215
	v_exp_f32_e32 v2, v2
	v_exp_f32_e32 v243, v243
	v_mov_b32_e32 v216, 0
	v_mov_b32_e32 v217, 0
	v_mov_b32_e32 v218, 0
	v_mov_b32_e32 v219, 0
	v_mul_f32_e32 v68, v68, v2
	v_mul_f32_e32 v69, v69, v2
	v_mul_f32_e32 v70, v70, v2
	v_mul_f32_e32 v71, v71, v2
	v_mul_f32_e32 v64, v64, v2
	v_mul_f32_e32 v65, v65, v2
	v_mul_f32_e32 v66, v66, v2
	v_mul_f32_e32 v67, v67, v2
	v_mul_f32_e32 v60, v60, v2
	v_mul_f32_e32 v61, v61, v2
	v_mul_f32_e32 v62, v62, v2
	v_mul_f32_e32 v63, v63, v2
	v_mul_f32_e32 v40, v40, v2
	v_mul_f32_e32 v41, v41, v2
	v_mul_f32_e32 v42, v42, v2
	v_mul_f32_e32 v43, v43, v2
	v_mul_f32_e32 v24, v24, v243
	v_mul_f32_e32 v25, v25, v243
	v_mul_f32_e32 v26, v26, v243
	v_mul_f32_e32 v27, v27, v243
	v_mul_f32_e32 v20, v20, v243
	v_mul_f32_e32 v21, v21, v243
	v_mul_f32_e32 v22, v22, v243
	v_mul_f32_e32 v23, v23, v243
	v_mul_f32_e32 v16, v16, v243
	v_mul_f32_e32 v17, v17, v243
	v_mul_f32_e32 v18, v18, v243
	v_mul_f32_e32 v19, v19, v243
	v_mul_f32_e32 v12, v12, v243
	v_mul_f32_e32 v13, v13, v243
	v_mul_f32_e32 v14, v14, v243
	v_mul_f32_e32 v15, v15, v243
	v_sub_f32_e32 v76, v76, v1
	v_sub_f32_e32 v77, v77, v1
	v_sub_f32_e32 v78, v78, v1
	v_sub_f32_e32 v79, v79, v1
	v_exp_f32_e32 v76, v76
	v_exp_f32_e32 v77, v77
	v_exp_f32_e32 v78, v78
	v_exp_f32_e32 v79, v79
	v_add_f32_e32 v216, v216, v76
	v_add_f32_e32 v218, v218, v77
	v_add_f32_e32 v216, v216, v78
	v_add_f32_e32 v218, v218, v79
	v_cvt_pk_bf16_f32 v76, v76, v77
	v_cvt_pk_bf16_f32 v77, v78, v79
	ds_write_b64 v247, v[76:77] offset:36864
	v_sub_f32_e32 v80, v80, v1
	v_sub_f32_e32 v81, v81, v1
	v_sub_f32_e32 v82, v82, v1
	v_sub_f32_e32 v83, v83, v1
	v_exp_f32_e32 v80, v80
	v_exp_f32_e32 v81, v81
	v_exp_f32_e32 v82, v82
	v_exp_f32_e32 v83, v83
	v_add_f32_e32 v216, v216, v80
	v_add_f32_e32 v218, v218, v81
	v_add_f32_e32 v216, v216, v82
	v_add_f32_e32 v218, v218, v83
	v_cvt_pk_bf16_f32 v80, v80, v81
	v_cvt_pk_bf16_f32 v81, v82, v83
	ds_write_b64 v247, v[80:81] offset:36896
	v_sub_f32_e32 v84, v84, v1
	v_sub_f32_e32 v85, v85, v1
	v_sub_f32_e32 v86, v86, v1
	v_sub_f32_e32 v87, v87, v1
	v_exp_f32_e32 v84, v84
	v_exp_f32_e32 v85, v85
	v_exp_f32_e32 v86, v86
	v_exp_f32_e32 v87, v87
	v_add_f32_e32 v216, v216, v84
	v_add_f32_e32 v218, v218, v85
	v_add_f32_e32 v216, v216, v86
	v_add_f32_e32 v218, v218, v87
	v_cvt_pk_bf16_f32 v84, v84, v85
	v_cvt_pk_bf16_f32 v85, v86, v87
	ds_write_b64 v247, v[84:85] offset:36928
	v_sub_f32_e32 v88, v88, v1
	v_sub_f32_e32 v89, v89, v1
	v_sub_f32_e32 v90, v90, v1
	v_sub_f32_e32 v91, v91, v1
	v_exp_f32_e32 v88, v88
	v_exp_f32_e32 v89, v89
	v_exp_f32_e32 v90, v90
	v_exp_f32_e32 v91, v91
	v_add_f32_e32 v216, v216, v88
	v_add_f32_e32 v218, v218, v89
	v_add_f32_e32 v216, v216, v90
	v_add_f32_e32 v218, v218, v91
	v_cvt_pk_bf16_f32 v88, v88, v89
	v_cvt_pk_bf16_f32 v89, v90, v91
	ds_write_b64 v247, v[88:89] offset:36960
	v_sub_f32_e32 v92, v92, v1
	v_sub_f32_e32 v93, v93, v1
	v_sub_f32_e32 v94, v94, v1
	v_sub_f32_e32 v95, v95, v1
	v_exp_f32_e32 v92, v92
	v_exp_f32_e32 v93, v93
	v_exp_f32_e32 v94, v94
	v_exp_f32_e32 v95, v95
	v_add_f32_e32 v216, v216, v92
	v_add_f32_e32 v218, v218, v93
	v_add_f32_e32 v216, v216, v94
	v_add_f32_e32 v218, v218, v95
	v_cvt_pk_bf16_f32 v92, v92, v93
	v_cvt_pk_bf16_f32 v93, v94, v95
	ds_write_b64 v247, v[92:93] offset:36992
	v_sub_f32_e32 v96, v96, v1
	v_sub_f32_e32 v97, v97, v1
	v_sub_f32_e32 v98, v98, v1
	v_sub_f32_e32 v99, v99, v1
	v_exp_f32_e32 v96, v96
	v_exp_f32_e32 v97, v97
	v_exp_f32_e32 v98, v98
	v_exp_f32_e32 v99, v99
	v_add_f32_e32 v216, v216, v96
	v_add_f32_e32 v218, v218, v97
	v_add_f32_e32 v216, v216, v98
	v_add_f32_e32 v218, v218, v99
	v_cvt_pk_bf16_f32 v96, v96, v97
	v_cvt_pk_bf16_f32 v97, v98, v99
	ds_write_b64 v247, v[96:97] offset:37024
	v_sub_f32_e32 v100, v100, v1
	v_sub_f32_e32 v101, v101, v1
	v_sub_f32_e32 v102, v102, v1
	v_sub_f32_e32 v103, v103, v1
	v_exp_f32_e32 v100, v100
	v_exp_f32_e32 v101, v101
	v_exp_f32_e32 v102, v102
	v_exp_f32_e32 v103, v103
	v_add_f32_e32 v216, v216, v100
	v_add_f32_e32 v218, v218, v101
	v_add_f32_e32 v216, v216, v102
	v_add_f32_e32 v218, v218, v103
	v_cvt_pk_bf16_f32 v100, v100, v101
	v_cvt_pk_bf16_f32 v101, v102, v103
	ds_write_b64 v247, v[100:101] offset:37056
	v_sub_f32_e32 v104, v104, v1
	v_sub_f32_e32 v105, v105, v1
	v_sub_f32_e32 v106, v106, v1
	v_sub_f32_e32 v107, v107, v1
	v_exp_f32_e32 v104, v104
	v_exp_f32_e32 v105, v105
	v_exp_f32_e32 v106, v106
	v_exp_f32_e32 v107, v107
	v_add_f32_e32 v216, v216, v104
	v_add_f32_e32 v218, v218, v105
	v_add_f32_e32 v216, v216, v106
	v_add_f32_e32 v218, v218, v107
	v_cvt_pk_bf16_f32 v104, v104, v105
	v_cvt_pk_bf16_f32 v105, v106, v107
	ds_write_b64 v247, v[104:105] offset:37088
	v_sub_f32_e32 v108, v108, v215
	v_sub_f32_e32 v109, v109, v215
	v_sub_f32_e32 v110, v110, v215
	v_sub_f32_e32 v111, v111, v215
	v_exp_f32_e32 v108, v108
	v_exp_f32_e32 v109, v109
	v_exp_f32_e32 v110, v110
	v_exp_f32_e32 v111, v111
	v_add_f32_e32 v217, v217, v108
	v_add_f32_e32 v219, v219, v109
	v_add_f32_e32 v217, v217, v110
	v_add_f32_e32 v219, v219, v111
	v_cvt_pk_bf16_f32 v108, v108, v109
	v_cvt_pk_bf16_f32 v109, v110, v111
	ds_write_b64 v247, v[108:109] offset:41216
	v_sub_f32_e32 v112, v112, v215
	v_sub_f32_e32 v113, v113, v215
	v_sub_f32_e32 v114, v114, v215
	v_sub_f32_e32 v115, v115, v215
	v_exp_f32_e32 v112, v112
	v_exp_f32_e32 v113, v113
	v_exp_f32_e32 v114, v114
	v_exp_f32_e32 v115, v115
	v_add_f32_e32 v217, v217, v112
	v_add_f32_e32 v219, v219, v113
	v_add_f32_e32 v217, v217, v114
	v_add_f32_e32 v219, v219, v115
	v_cvt_pk_bf16_f32 v112, v112, v113
; #define LAS __attribute__((address_space(3)))
; DEV void attn_item(const Fr& F, int l, int b, int qb, int kvh, bool ctxq) {
;     ...
;         __builtin_amdgcn_wave_barrier();
;         const int clo = nlo >> 1, chi = nhi >> 1;
; #pragma unroll
;         for (int c = 0; c < 4; ++c) { if (c >= clo && c < chi) {
;             const bf16x8 p0 = *(const LAS bf16x8*)(Pw + fr * 136 + 32 * c + 8 * fq), p1 = *(const LAS bf16x8*)(Pw + (16 + fr) * 136 + 32 * c + 8 * fq);
; #pragma unroll
;             for (int n2 = 0; n2 < 4; ++n2) { const bf16x8 vf = tr_frag(Vs, 72, 32 * c, 16 * n2, F.lane);
;                 O[0][n2] = __builtin_amdgcn_mfma_f32_16x16x32_bf16(vf, p0, O[0][n2], 0, 0, 0); O[1][n2] = __builtin_amdgcn_mfma_f32_16x16x32_bf16(vf, p1, O[1][n2], 0, 0, 0); } } }
	v_cvt_pk_bf16_f32 v113, v114, v115
	ds_write_b64 v247, v[112:113] offset:41248
	v_sub_f32_e32 v116, v116, v215
	v_sub_f32_e32 v117, v117, v215
	v_sub_f32_e32 v118, v118, v215
	v_sub_f32_e32 v119, v119, v215
	v_exp_f32_e32 v116, v116
	v_exp_f32_e32 v117, v117
	v_exp_f32_e32 v118, v118
	v_exp_f32_e32 v119, v119
	v_add_f32_e32 v217, v217, v116
	v_add_f32_e32 v219, v219, v117
	v_add_f32_e32 v217, v217, v118
	v_add_f32_e32 v219, v219, v119
	v_cvt_pk_bf16_f32 v116, v116, v117
	v_cvt_pk_bf16_f32 v117, v118, v119
	ds_write_b64 v247, v[116:117] offset:41280
	v_sub_f32_e32 v120, v120, v215
	v_sub_f32_e32 v121, v121, v215
	v_sub_f32_e32 v122, v122, v215
	v_sub_f32_e32 v123, v123, v215
	v_exp_f32_e32 v120, v120
	v_exp_f32_e32 v121, v121
	v_exp_f32_e32 v122, v122
	v_exp_f32_e32 v123, v123
	v_add_f32_e32 v217, v217, v120
	v_add_f32_e32 v219, v219, v121
	v_add_f32_e32 v217, v217, v122
	v_add_f32_e32 v219, v219, v123
	v_cvt_pk_bf16_f32 v120, v120, v121
	v_cvt_pk_bf16_f32 v121, v122, v123
	ds_write_b64 v247, v[120:121] offset:41312
	v_sub_f32_e32 v124, v124, v215
	v_sub_f32_e32 v125, v125, v215
	v_sub_f32_e32 v126, v126, v215
	v_sub_f32_e32 v127, v127, v215
	v_exp_f32_e32 v124, v124
	v_exp_f32_e32 v125, v125
	v_exp_f32_e32 v126, v126
	v_exp_f32_e32 v127, v127
	v_add_f32_e32 v217, v217, v124
	v_add_f32_e32 v219, v219, v125
	v_add_f32_e32 v217, v217, v126
	v_add_f32_e32 v219, v219, v127
	v_cvt_pk_bf16_f32 v124, v124, v125
	v_cvt_pk_bf16_f32 v125, v126, v127
	ds_write_b64 v247, v[124:125] offset:41344
	v_sub_f32_e32 v128, v128, v215
	v_sub_f32_e32 v129, v129, v215
	v_sub_f32_e32 v130, v130, v215
	v_sub_f32_e32 v131, v131, v215
	v_exp_f32_e32 v128, v128
	v_exp_f32_e32 v129, v129
	v_exp_f32_e32 v130, v130
	v_exp_f32_e32 v131, v131
	v_add_f32_e32 v217, v217, v128
	v_add_f32_e32 v219, v219, v129
	v_add_f32_e32 v217, v217, v130
	v_add_f32_e32 v219, v219, v131
	v_cvt_pk_bf16_f32 v128, v128, v129
	v_cvt_pk_bf16_f32 v129, v130, v131
	ds_write_b64 v247, v[128:129] offset:41376
	v_sub_f32_e32 v132, v132, v215
	v_sub_f32_e32 v133, v133, v215
	v_sub_f32_e32 v134, v134, v215
	v_sub_f32_e32 v135, v135, v215
	v_exp_f32_e32 v132, v132
	v_exp_f32_e32 v133, v133
	v_exp_f32_e32 v134, v134
	v_exp_f32_e32 v135, v135
	v_add_f32_e32 v217, v217, v132
	v_add_f32_e32 v219, v219, v133
	v_add_f32_e32 v217, v217, v134
	v_add_f32_e32 v219, v219, v135
	v_cvt_pk_bf16_f32 v132, v132, v133
	v_cvt_pk_bf16_f32 v133, v134, v135
	ds_write_b64 v247, v[132:133] offset:41408
	v_sub_f32_e32 v136, v136, v215
	v_sub_f32_e32 v137, v137, v215
	v_sub_f32_e32 v138, v138, v215
	v_sub_f32_e32 v139, v139, v215
	v_exp_f32_e32 v136, v136
	v_exp_f32_e32 v137, v137
	v_exp_f32_e32 v138, v138
	v_exp_f32_e32 v139, v139
	v_add_f32_e32 v217, v217, v136
	v_add_f32_e32 v219, v219, v137
	v_add_f32_e32 v217, v217, v138
	v_add_f32_e32 v219, v219, v139
	v_cvt_pk_bf16_f32 v136, v136, v137
	v_cvt_pk_bf16_f32 v137, v138, v139
	ds_write_b64 v247, v[136:137] offset:41440
	v_add_f32_e32 v216, v216, v218
	v_add_f32_e32 v217, v217, v219
	s_waitcnt lgkmcnt(0)
	ds_read_b128 v[80:83], v248 offset:36864
	ds_read_b128 v[84:87], v248 offset:41216
	ds_read_b64_tr_b16 v[88:89], v249 offset:18432
	ds_read_b64_tr_b16 v[90:91], v249 offset:19008
	ds_read_b64_tr_b16 v[92:93], v249 offset:18464
	ds_read_b64_tr_b16 v[94:95], v249 offset:19040
	ds_read_b64_tr_b16 v[96:97], v249 offset:18496
	ds_read_b64_tr_b16 v[98:99], v249 offset:19072
	ds_read_b64_tr_b16 v[100:101], v249 offset:18528
	ds_read_b64_tr_b16 v[102:103], v249 offset:19104
	ds_read_b128 v[112:115], v248 offset:36928
	ds_read_b128 v[116:119], v248 offset:41280
	ds_read_b64_tr_b16 v[120:121], v249 offset:23040
	ds_read_b64_tr_b16 v[122:123], v249 offset:23616
	ds_read_b64_tr_b16 v[124:125], v249 offset:23072
	ds_read_b64_tr_b16 v[126:127], v249 offset:23648
	ds_read_b64_tr_b16 v[128:129], v249 offset:23104
	ds_read_b64_tr_b16 v[130:131], v249 offset:23680
	ds_read_b64_tr_b16 v[132:133], v249 offset:23136
	ds_read_b64_tr_b16 v[134:135], v249 offset:23712
	s_waitcnt lgkmcnt(10)
	v_mfma_f32_16x16x32_bf16 v[68:71], v[88:91], v[80:83], v[68:71]
	v_mfma_f32_16x16x32_bf16 v[24:27], v[88:91], v[84:87], v[24:27]
	v_mfma_f32_16x16x32_bf16 v[64:67], v[92:95], v[80:83], v[64:67]
	v_mfma_f32_16x16x32_bf16 v[20:23], v[92:95], v[84:87], v[20:23]
	v_mfma_f32_16x16x32_bf16 v[60:63], v[96:99], v[80:83], v[60:63]
	v_mfma_f32_16x16x32_bf16 v[16:19], v[96:99], v[84:87], v[16:19]
	v_mfma_f32_16x16x32_bf16 v[40:43], v[100:103], v[80:83], v[40:43]
	v_mfma_f32_16x16x32_bf16 v[12:15], v[100:103], v[84:87], v[12:15]
	ds_read_b128 v[80:83], v248 offset:36992
	ds_read_b128 v[84:87], v248 offset:41344
	ds_read_b64_tr_b16 v[88:89], v249 offset:27648
	ds_read_b64_tr_b16 v[90:91], v249 offset:28224
	ds_read_b64_tr_b16 v[92:93], v249 offset:27680
	ds_read_b64_tr_b16 v[94:95], v249 offset:28256
	ds_read_b64_tr_b16 v[96:97], v249 offset:27712
	ds_read_b64_tr_b16 v[98:99], v249 offset:28288
	ds_read_b64_tr_b16 v[100:101], v249 offset:27744
	ds_read_b64_tr_b16 v[102:103], v249 offset:28320
	s_waitcnt lgkmcnt(10)
; DEV unsigned pk2(float lo, float hi) { unsigned r; asm("v_cvt_pk_bf16_f32 %0, %1, %2" : "=v"(r) : "v"(lo), "v"(hi)); return r; }
; DEV void attn_item(const Fr& F, int l, int b, int qb, int kvh, bool ctxq) {
;     ...
;             sum += __shfl_xor(sum, 16); sum += __shfl_xor(sum, 32);
;             lrow[mt] = lrow[mt] * scl[mt] + sum; mrow[mt] = mn;
;     ...
; #pragma unroll
;     for (int mt = 0; mt < 2; ++mt) { const int t = r0 + mt * 16 + fr; const float rl = 1.f / lrow[mt];
; #pragma unroll
;         for (int n2 = 0; n2 < 4; ++n2) { u32x2 wv; wv.x = pk2(O[mt][n2][0] * rl, O[mt][n2][1] * rl); wv.y = pk2(O[mt][n2][2] * rl, O[mt][n2][3] * rl);
;             *(u32x2*)(F.MIX + (size_t)(qrow0 + t) * D + 512 + (kvh * 2 + g) * 64 + n2 * 16 + 4 * fq) = wv; } }
	v_mfma_f32_16x16x32_bf16 v[68:71], v[120:123], v[112:115], v[68:71]
	v_mfma_f32_16x16x32_bf16 v[24:27], v[120:123], v[116:119], v[24:27]
	v_mfma_f32_16x16x32_bf16 v[64:67], v[124:127], v[112:115], v[64:67]
	v_mfma_f32_16x16x32_bf16 v[20:23], v[124:127], v[116:119], v[20:23]
	v_mfma_f32_16x16x32_bf16 v[60:63], v[128:131], v[112:115], v[60:63]
	v_mfma_f32_16x16x32_bf16 v[16:19], v[128:131], v[116:119], v[16:19]
	v_mfma_f32_16x16x32_bf16 v[40:43], v[132:135], v[112:115], v[40:43]
	v_mfma_f32_16x16x32_bf16 v[12:15], v[132:135], v[116:119], v[12:15]
	ds_read_b128 v[112:115], v248 offset:37056
	ds_read_b128 v[116:119], v248 offset:41408
	ds_read_b64_tr_b16 v[120:121], v249 offset:32256
	ds_read_b64_tr_b16 v[122:123], v249 offset:32832
	ds_read_b64_tr_b16 v[124:125], v249 offset:32288
	ds_read_b64_tr_b16 v[126:127], v249 offset:32864
	ds_read_b64_tr_b16 v[128:129], v249 offset:32320
	ds_read_b64_tr_b16 v[130:131], v249 offset:32896
	ds_read_b64_tr_b16 v[132:133], v249 offset:32352
	ds_read_b64_tr_b16 v[134:135], v249 offset:32928
	s_waitcnt lgkmcnt(10)
	v_mfma_f32_16x16x32_bf16 v[68:71], v[88:91], v[80:83], v[68:71]
	v_mfma_f32_16x16x32_bf16 v[24:27], v[88:91], v[84:87], v[24:27]
	v_mfma_f32_16x16x32_bf16 v[64:67], v[92:95], v[80:83], v[64:67]
	v_mfma_f32_16x16x32_bf16 v[20:23], v[92:95], v[84:87], v[20:23]
	v_mfma_f32_16x16x32_bf16 v[60:63], v[96:99], v[80:83], v[60:63]
	v_mfma_f32_16x16x32_bf16 v[16:19], v[96:99], v[84:87], v[16:19]
	v_mfma_f32_16x16x32_bf16 v[40:43], v[100:103], v[80:83], v[40:43]
	v_mfma_f32_16x16x32_bf16 v[12:15], v[100:103], v[84:87], v[12:15]
	s_waitcnt lgkmcnt(0)
	v_mfma_f32_16x16x32_bf16 v[68:71], v[120:123], v[112:115], v[68:71]
	v_mfma_f32_16x16x32_bf16 v[24:27], v[120:123], v[116:119], v[24:27]
	v_mfma_f32_16x16x32_bf16 v[64:67], v[124:127], v[112:115], v[64:67]
	v_mfma_f32_16x16x32_bf16 v[20:23], v[124:127], v[116:119], v[20:23]
	v_mfma_f32_16x16x32_bf16 v[60:63], v[128:131], v[112:115], v[60:63]
	v_mfma_f32_16x16x32_bf16 v[16:19], v[128:131], v[116:119], v[16:19]
	v_mfma_f32_16x16x32_bf16 v[40:43], v[132:135], v[112:115], v[40:43]
	v_mfma_f32_16x16x32_bf16 v[12:15], v[132:135], v[116:119], v[12:15]
	ds_bpermute_b32 v252, v245, v216
	ds_bpermute_b32 v253, v245, v217
	s_waitcnt lgkmcnt(0)
	v_add_f32_e32 v216, v216, v252
	v_add_f32_e32 v217, v217, v253
	ds_bpermute_b32 v252, v246, v216
	ds_bpermute_b32 v253, v246, v217
	v_mov_b32_e32 v78, 0
	v_mov_b32_e32 v108, 0
	v_mov_b32_e32 v76, v243
	v_mov_b32_e32 v109, v215
	s_waitcnt lgkmcnt(0)
	v_add_f32_e32 v3, v216, v252
	v_add_f32_e32 v77, v217, v253
.LBB0_696:
	s_waitcnt lgkmcnt(0)
	v_add_f32_e32 v77, v77, v78
	v_add_f32_e32 v3, v3, v108
	v_fmac_f32_e32 v77, v171, v76
	s_cmp_lt_i32 s64, 5
	v_fmac_f32_e32 v3, v169, v2
	s_cbranch_scc0 .LBB0_701
	v_mov_b32_e32 v175, v109
	v_mov_b32_e32 v177, v1
	v_mov_b32_e32 v171, v77
	v_mov_b32_e32 v169, v3
	s_mov_b32 s65, s64
	s_branch .LBB0_501
.LBB0_701:
	v_div_scale_f32 v1, s[6:7], v3, v3, 1.0
	v_rcp_f32_e32 v2, v1
	v_readlane_b32 s6, v237, 5
	v_readlane_b32 s7, v238, 48
	s_add_i32 s6, s6, s7
	v_fma_f32 v4, -v1, v2, 1.0
	v_fmac_f32_e32 v2, v4, v2
	v_div_scale_f32 v4, vcc, 1.0, v3, 1.0
	v_mul_f32_e32 v5, v4, v2
	v_fma_f32 v6, -v1, v5, v4
	v_fmac_f32_e32 v5, v6, v2
	v_fma_f32 v1, -v1, v5, v4
	s_lshl_b32 s6, s6, 6
	v_div_fmas_f32 v1, v1, v2, v5
	v_readlane_b32 s40, v239, 25
	s_ashr_i32 s7, s6, 31
	v_div_fixup_f32 v1, v1, v3, 1.0
	v_lshlrev_b64 v[2:3], 11, v[180:181]
	v_readlane_b32 s41, v239, 26
	v_mul_f32_e32 v4, v1, v68
	v_mul_f32_e32 v5, v1, v69
	v_lshl_add_u64 v[2:3], s[40:41], 0, v[2:3]
	s_lshl_b64 s[6:7], s[6:7], 1
	v_cvt_pk_bf16_f32 v4, v4, v5
	v_mul_f32_e32 v5, v1, v70
	v_lshl_add_u64 v[2:3], v[2:3], 0, s[6:7]
	v_mov_b32_e32 v177, v0
	v_mul_f32_e32 v6, v1, v71
	v_cvt_pk_bf16_f32 v5, v5, v6
	v_lshl_add_u64 v[2:3], v[2:3], 0, v[176:177]
	global_store_dwordx2 v[2:3], v[4:5], off offset:1024
	v_mul_f32_e32 v4, v1, v64
	v_mul_f32_e32 v5, v1, v65
	v_cvt_pk_bf16_f32 v4, v4, v5
	v_mul_f32_e32 v5, v1, v66
	v_mul_f32_e32 v6, v1, v67
	v_cvt_pk_bf16_f32 v5, v5, v6
	global_store_dwordx2 v[2:3], v[4:5], off offset:1056
	v_mul_f32_e32 v4, v1, v60
	v_mul_f32_e32 v5, v1, v61
	v_cvt_pk_bf16_f32 v4, v4, v5
	v_mul_f32_e32 v5, v1, v62
	v_mul_f32_e32 v6, v1, v63
	v_cvt_pk_bf16_f32 v5, v5, v6
	v_div_scale_f32 v6, s[38:39], v77, v77, 1.0
	v_rcp_f32_e32 v7, v6
	global_store_dwordx2 v[2:3], v[4:5], off offset:1088
	v_mul_f32_e32 v4, v1, v40
	v_mul_f32_e32 v5, v1, v41
	v_cvt_pk_bf16_f32 v4, v4, v5
	v_mul_f32_e32 v5, v1, v42
	v_mul_f32_e32 v1, v1, v43
	v_cvt_pk_bf16_f32 v5, v5, v1
	v_fma_f32 v1, -v6, v7, 1.0
	v_fmac_f32_e32 v7, v1, v7
	v_div_scale_f32 v1, vcc, 1.0, v77, 1.0
	global_store_dwordx2 v[2:3], v[4:5], off offset:1120
	v_mul_f32_e32 v2, v1, v7
	v_fma_f32 v3, -v6, v2, v1
	v_fmac_f32_e32 v2, v3, v7
	v_fma_f32 v1, -v6, v2, v1
	v_div_fmas_f32 v1, v1, v7, v2
	v_or_b32_e32 v2, 16, v180
	v_ashrrev_i32_e32 v3, 31, v2
	v_div_fixup_f32 v1, v1, v77, 1.0
	v_lshlrev_b64 v[2:3], 11, v[2:3]
	v_mul_f32_e32 v4, v1, v24
	v_mul_f32_e32 v5, v1, v25
	v_lshl_add_u64 v[2:3], s[40:41], 0, v[2:3]
	v_cvt_pk_bf16_f32 v4, v4, v5
	v_mul_f32_e32 v5, v1, v26
	v_lshl_add_u64 v[2:3], v[2:3], 0, s[6:7]
	v_mul_f32_e32 v6, v1, v27
	v_cvt_pk_bf16_f32 v5, v5, v6
	v_lshl_add_u64 v[2:3], v[2:3], 0, v[176:177]
	global_store_dwordx2 v[2:3], v[4:5], off offset:1024
	v_mul_f32_e32 v4, v1, v20
	v_mul_f32_e32 v5, v1, v21
	v_cvt_pk_bf16_f32 v4, v4, v5
	v_mul_f32_e32 v5, v1, v22
	v_mul_f32_e32 v6, v1, v23
	v_cvt_pk_bf16_f32 v5, v5, v6
	global_store_dwordx2 v[2:3], v[4:5], off offset:1056
	v_mul_f32_e32 v4, v1, v16
	v_mul_f32_e32 v5, v1, v17
	v_cvt_pk_bf16_f32 v4, v4, v5
	v_mul_f32_e32 v5, v1, v18
	v_mul_f32_e32 v6, v1, v19
	v_cvt_pk_bf16_f32 v5, v5, v6
	global_store_dwordx2 v[2:3], v[4:5], off offset:1088
	v_mul_f32_e32 v4, v1, v12
	v_mul_f32_e32 v5, v1, v13
	v_cvt_pk_bf16_f32 v4, v4, v5
	v_mul_f32_e32 v5, v1, v14
	s_mov_b64 s[6:7], -1
	v_mul_f32_e32 v1, v1, v15
	v_cvt_pk_bf16_f32 v5, v5, v1
	global_store_dwordx2 v[2:3], v[4:5], off offset:1120
	s_barrier

; __global__ void __launch_bounds__(NTHR, 2) fwd_megakernel(Args args) {
;     extern __shared__ __attribute__((aligned(16))) unsigned char lds_raw[];
;     cg::grid_group grid = cg::this_grid();
	.amdhsa_kernel _Z14fwd_megakernel4Args
		.amdhsa_group_segment_fixed_size 0
		.amdhsa_private_segment_fixed_size 0
		.amdhsa_kernarg_size 424
		.amdhsa_user_sgpr_count 2
		.amdhsa_user_sgpr_dispatch_ptr 0
		.amdhsa_user_sgpr_queue_ptr 0
		.amdhsa_user_sgpr_kernarg_segment_ptr 1
		.amdhsa_user_sgpr_dispatch_id 0
		.amdhsa_user_sgpr_kernarg_preload_length 0
		.amdhsa_user_sgpr_kernarg_preload_offset 0
		.amdhsa_user_sgpr_private_segment_size 0
		.amdhsa_uses_dynamic_stack 0
		.amdhsa_enable_private_segment 0
		.amdhsa_system_sgpr_workgroup_id_x 1
		.amdhsa_system_sgpr_workgroup_id_y 0
		.amdhsa_system_sgpr_workgroup_id_z 0
		.amdhsa_system_sgpr_workgroup_info 0
		.amdhsa_system_vgpr_workitem_id 2
		.amdhsa_next_free_vgpr 256
		.amdhsa_next_free_sgpr 102
		.amdhsa_accum_offset 256
		.amdhsa_reserve_vcc 1
		.amdhsa_float_round_mode_32 0
		.amdhsa_float_round_mode_16_64 0
		.amdhsa_float_denorm_mode_32 3
		.amdhsa_float_denorm_mode_16_64 3
		.amdhsa_dx10_clamp 1
		.amdhsa_ieee_mode 1
		.amdhsa_fp16_overflow 0
		.amdhsa_tg_split 0
		.amdhsa_exception_fp_ieee_invalid_op 0
		.amdhsa_exception_fp_denorm_src 0
		.amdhsa_exception_fp_ieee_div_zero 0
		.amdhsa_exception_fp_ieee_overflow 0
		.amdhsa_exception_fp_ieee_underflow 0
		.amdhsa_exception_fp_ieee_inexact 0
		.amdhsa_exception_int_div_zero 0
	.end_amdhsa_kernel

; __global__ void __launch_bounds__(NTHR, 2) fwd_megakernel(Args args) {
;     extern __shared__ __attribute__((aligned(16))) unsigned char lds_raw[];
;     cg::grid_group grid = cg::this_grid();
amdhsa.kernels:
  - .agpr_count:     0
    .args:
      - .offset:         0
        .size:           168
        .value_kind:     by_value
      - .offset:         168
        .size:           4
        .value_kind:     hidden_block_count_x
      - .offset:         172
        .size:           4
        .value_kind:     hidden_block_count_y
      - .offset:         176
        .size:           4
        .value_kind:     hidden_block_count_z
      - .offset:         180
        .size:           2
        .value_kind:     hidden_group_size_x
      - .offset:         182
        .size:           2
        .value_kind:     hidden_group_size_y
      - .offset:         184
        .size:           2
        .value_kind:     hidden_group_size_z
      - .offset:         186
        .size:           2
        .value_kind:     hidden_remainder_x
      - .offset:         188
        .size:           2
        .value_kind:     hidden_remainder_y
      - .offset:         190
        .size:           2
        .value_kind:     hidden_remainder_z
      - .offset:         208
        .size:           8
        .value_kind:     hidden_global_offset_x
      - .offset:         216
        .size:           8
        .value_kind:     hidden_global_offset_y
      - .offset:         224
        .size:           8
        .value_kind:     hidden_global_offset_z
      - .offset:         232
        .size:           2
        .value_kind:     hidden_grid_dims
      - .offset:         256
        .size:           8
        .value_kind:     hidden_multigrid_sync_arg
      - .offset:         288
        .size:           4
        .value_kind:     hidden_dynamic_lds_size
    .group_segment_fixed_size: 0
    .kernarg_segment_align: 8
    .kernarg_segment_size: 424
    .language:       OpenCL C
    .language_version:
      - 2
      - 0
    .max_flat_workgroup_size: 512
    .name:           _Z14fwd_megakernel4Args
    .private_segment_fixed_size: 0
    .sgpr_count:     108
    .sgpr_spill_count: 510
    .symbol:         _Z14fwd_megakernel4Args.kd
    .uniform_work_group_size: 1
    .uses_dynamic_stack: false
    .vgpr_count:     256
    .vgpr_spill_count: 0
    .wavefront_size: 64
